# phase-3 compress tiles split-K over 4 workgroups (3 idle helpers write fp32 partials write-through, owner adds them in fp32) on top of the faster latent-norm loop
# baseline (speedup 1.0000x reference)
.LBB0_1305:
	v_readlane_b32 s0, v252, 30
	v_readlane_b32 s1, v252, 31
	v_readlane_b32 s80, v254, 19
	v_readlane_b32 s74, v254, 25
	s_andn2_b64 vcc, exec, s[0:1]
	v_readlane_b32 s81, v254, 20
	v_readlane_b32 s75, v254, 26
	s_mov_b32 s25, 0x8000
	s_movk_i32 s34, 0x3fff
	s_mov_b32 s26, 0
	s_mov_b32 s27, 0
	s_mov_b64 s[28:29], 0
	s_cmpk_lg_i32 s90, 0x200
	s_cbranch_scc1 .Lsk_nosplit
	s_mov_b32 s27, 24
	v_readlane_b32 s31, v251, 24
	s_nop 1
	s_sub_i32 s30, s31, 192
	s_mov_b32 s26, 1
	s_cmp_lt_u32 s30, 64
	s_cbranch_scc1 .Lsk_help
	s_sub_i32 s30, s31, 448
	s_mov_b32 s26, 2
	s_cmp_lt_u32 s30, 64
	s_cbranch_scc1 .Lsk_help
	s_sub_i32 s30, s31, 256
	s_mov_b32 s26, 3
	s_cmp_lt_u32 s30, 64
	s_cbranch_scc1 .Lsk_help
	s_mov_b32 s26, 0
	s_branch .Lsk_nosplit
.Lsk_help:
	s_lshl_b32 s28, s26, 10
	s_branch .Lsk_enter
.Lsk_nosplit:
	s_cbranch_vccnz .LBB0_1574
.Lsk_enter:
	s_add_u32 s12, s16, 0x5800000
	s_addc_u32 s13, s17, 0
	s_add_u32 s14, s16, 0xe000000
	s_addc_u32 s15, s17, 0
	s_add_u32 s2, s16, 0xe280000
	v_lshlrev_b32_e32 v192, 2, v56
	v_readlane_b32 s4, v254, 10
	s_addc_u32 s3, s17, 0
	v_or_b32_e32 v195, 1, v192
	v_or_b32_e32 v210, 2, v192
	v_or_b32_e32 v211, 3, v192
	v_or_b32_e32 v212, 8, v192
	v_or_b32_e32 v213, 9, v192
	v_or_b32_e32 v214, 10, v192
	v_or_b32_e32 v215, 11, v192
	v_or_b32_e32 v216, 16, v192
	v_or_b32_e32 v217, 17, v192
	v_or_b32_e32 v218, 18, v192
	v_or_b32_e32 v219, 19, v192
	v_or_b32_e32 v220, 24, v192
	v_or_b32_e32 v221, 25, v192
	v_or_b32_e32 v222, 26, v192
	v_or_b32_e32 v223, 27, v192
	v_or_b32_e32 v224, 32, v192
	v_or_b32_e32 v225, 33, v192
	v_or_b32_e32 v226, 34, v192
	v_or_b32_e32 v227, 35, v192
	v_or_b32_e32 v228, 40, v192
	v_or_b32_e32 v229, 41, v192
	v_or_b32_e32 v230, 42, v192
	v_or_b32_e32 v231, 43, v192
	v_or_b32_e32 v232, 48, v192
	v_or_b32_e32 v233, 49, v192
	v_or_b32_e32 v234, 50, v192
	v_or_b32_e32 v235, 51, v192
	v_or_b32_e32 v236, 56, v192
	v_or_b32_e32 v237, 57, v192
	v_or_b32_e32 v238, 58, v192
	v_or_b32_e32 v239, 59, v192
	v_lshl_or_b32 v240, v54, 6, v55
	v_readlane_b32 s5, v254, 11
	v_readlane_b32 s18, v251, 24
	s_nop 0
	s_cmp_lg_u32 s26, 0
	s_cselect_b32 s18, s30, s18
	s_branch .LBB0_1308
.LBB0_1308:
	s_ashr_i32 s6, s18, 5
	s_bfe_u32 s19, s18, 0x40001
	s_ashr_i32 s7, s6, 31
	s_lshl_b32 s8, s19, 18
	s_and_b32 s20, s18, 1
	s_lshl_b64 s[0:1], s[6:7], 22
	s_add_u32 s9, s12, s0
	s_addc_u32 s11, s13, s1
	s_add_u32 s10, s9, s8
	s_addc_u32 s11, s11, 0
	v_cndmask_b32_e64 v0, 0, 1, s[4:5]
	s_cmp_lt_u32 s18, 32
	s_mov_b32 s9, 0x540000
	v_lshlrev_b32_e32 v1, 19, v0
	v_mov_b32_e32 v0, v161
	s_cselect_b32 s9, s9, 0x640000
	v_mov_b32_e32 v17, v186
	s_add_u32 s22, s16, s9
	s_addc_u32 s23, s17, 0
	v_lshlrev_b32_e32 v2, 4, v17
	s_lshl_b32 s24, s20, 19
	v_ashrrev_i32_e32 v18, 3, v17
	v_and_b32_e32 v16, 0x70, v2
	s_add_u32 s22, s22, s24
	v_lshl_or_b32 v160, v18, 11, v16
	v_lshl_or_b32 v6, v18, 12, v16
	s_addc_u32 s23, s23, 0
	v_add_u32_e32 v2, 0x10000, v160
	v_add_u32_e32 v4, 0x20000, v160
	s_waitcnt vmcnt(0)
	v_add_u32_e32 v8, 0x30000, v160
	v_add_u32_e32 v10, 0x20000, v6
	v_add_u32_e32 v12, 0x40000, v6
	s_add_u32 s10, s10, s28
	s_addc_u32 s11, s11, 0
	s_add_u32 s22, s22, s28
	s_addc_u32 s23, s23, 0
	s_barrier
	global_load_dwordx4 v[64:67], v160, s[10:11]
	global_load_dwordx4 v[68:71], v2, s[10:11]
	global_load_dwordx4 v[72:75], v4, s[10:11]
	global_load_dwordx4 v[76:79], v8, s[10:11]
	global_load_dwordx4 v[80:83], v6, s[22:23]
	global_load_dwordx4 v[92:95], v10, s[22:23]
	global_load_dwordx4 v[100:103], v12, s[22:23]
	v_add_u32_e32 v14, 0x60000, v6
	global_load_dwordx4 v[112:115], v14, s[22:23]
	global_load_dwordx4 v[84:87], v160, s[10:11] offset:128
	global_load_dwordx4 v[88:91], v2, s[10:11] offset:128
	global_load_dwordx4 v[96:99], v4, s[10:11] offset:128
	global_load_dwordx4 v[104:107], v8, s[10:11] offset:128
	global_load_dwordx4 v[108:111], v6, s[22:23] offset:128
	global_load_dwordx4 v[116:119], v10, s[22:23] offset:128
	global_load_dwordx4 v[120:123], v12, s[22:23] offset:128
	global_load_dwordx4 v[124:127], v14, s[22:23] offset:128
	v_mad_u64_u32 v[164:165], s[10:11], v18, s43, v[16:17]
	v_and_b32_e32 v18, 0x5f, v17
	v_lshrrev_b32_e32 v19, 1, v17
	v_and_b32_e32 v17, 31, v17
	v_and_b32_e32 v16, 16, v19
	v_and_or_b32 v17, v19, s44, v17
	v_mov_b32_e32 v3, v161
	v_mov_b32_e32 v5, v161
	v_mov_b32_e32 v9, v161
	v_mov_b32_e32 v7, v161
	v_mov_b32_e32 v11, v161
	v_mov_b32_e32 v13, v161
	v_mov_b32_e32 v15, v161
	v_mad_u32_u24 v165, v18, s43, v16
	v_mad_u64_u32 v[166:167], s[10:11], v17, s43, v[16:17]
	v_or_b32_e32 v16, s9, v1
	v_mov_b32_e32 v17, v161
	s_or_b32 s0, s0, s8
	s_mov_b32 s21, s27
	v_add_u32_e32 v167, 0xd800, v164
	v_lshl_add_u64 v[168:169], v[16:17], 0, v[14:15]
	v_lshl_add_u64 v[170:171], v[16:17], 0, v[12:13]
	v_lshl_add_u64 v[172:173], v[16:17], 0, v[10:11]
	v_lshl_add_u64 v[174:175], v[16:17], 0, v[6:7]
	v_lshl_add_u64 v[176:177], s[0:1], 0, v[8:9]
	v_lshl_add_u64 v[178:179], s[0:1], 0, v[4:5]
	v_lshl_add_u64 v[180:181], s[0:1], 0, v[2:3]
	v_lshl_add_u64 v[182:183], s[0:1], 0, v[160:161]
	v_lshl_add_u64 v[168:169], v[168:169], 0, s[28:29]
	v_lshl_add_u64 v[170:171], v[170:171], 0, s[28:29]
	v_lshl_add_u64 v[172:173], v[172:173], 0, s[28:29]
	v_lshl_add_u64 v[174:175], v[174:175], 0, s[28:29]
	v_lshl_add_u64 v[176:177], v[176:177], 0, s[28:29]
	v_lshl_add_u64 v[178:179], v[178:179], 0, s[28:29]
	v_lshl_add_u64 v[180:181], v[180:181], 0, s[28:29]
	v_lshl_add_u64 v[182:183], v[182:183], 0, s[28:29]
	v_mov_b32_e32 v1, v0
	v_mov_b32_e32 v2, v0
	v_mov_b32_e32 v3, v0
	v_mov_b32_e32 v4, v0
	v_mov_b32_e32 v5, v0
	v_mov_b32_e32 v6, v0
	v_mov_b32_e32 v7, v0
	v_mov_b32_e32 v8, v0
	v_mov_b32_e32 v9, v0
	v_mov_b32_e32 v10, v0
	v_mov_b32_e32 v11, v0
	v_mov_b32_e32 v12, v0
	v_mov_b32_e32 v13, v0
	v_mov_b32_e32 v14, v0
	v_mov_b32_e32 v15, v0
	v_mov_b32_e32 v16, v0
	v_mov_b32_e32 v17, v0
	v_mov_b32_e32 v18, v0
	v_mov_b32_e32 v19, v0
	v_mov_b32_e32 v20, v0
	v_mov_b32_e32 v21, v0
	v_mov_b32_e32 v22, v0
	v_mov_b32_e32 v23, v0
	v_mov_b32_e32 v24, v0
	v_mov_b32_e32 v25, v0
	v_mov_b32_e32 v26, v0
	v_mov_b32_e32 v27, v0
	v_mov_b32_e32 v28, v0
	v_mov_b32_e32 v29, v0
	v_mov_b32_e32 v30, v0
	v_mov_b32_e32 v31, v0
	v_mov_b32_e32 v32, v0
	v_mov_b32_e32 v33, v0
	v_mov_b32_e32 v34, v0
	v_mov_b32_e32 v35, v0
	v_mov_b32_e32 v36, v0
	v_mov_b32_e32 v37, v0
	v_mov_b32_e32 v38, v0
	v_mov_b32_e32 v39, v0
	v_mov_b32_e32 v40, v0
	v_mov_b32_e32 v41, v0
	v_mov_b32_e32 v42, v0
	v_mov_b32_e32 v43, v0
	v_mov_b32_e32 v44, v0
	v_mov_b32_e32 v45, v0
	v_mov_b32_e32 v46, v0
	v_mov_b32_e32 v47, v0
	v_mov_b32_e32 v48, v0
	v_mov_b32_e32 v49, v0
	v_mov_b32_e32 v50, v0
	v_mov_b32_e32 v51, v0
	v_mov_b32_e32 v52, v0
	v_mov_b32_e32 v53, v0
	v_mov_b32_e32 v54, v0
	v_mov_b32_e32 v55, v0
	v_mov_b32_e32 v56, v0
	v_mov_b32_e32 v57, v0
	v_mov_b32_e32 v58, v0
	v_mov_b32_e32 v59, v0
	v_mov_b32_e32 v60, v0
	v_mov_b32_e32 v61, v0
	v_mov_b32_e32 v62, v0
	v_mov_b32_e32 v63, v0
	s_waitcnt vmcnt(15)
	ds_write_b128 v164, v[64:67]
	s_waitcnt vmcnt(14)
	ds_write_b128 v164, v[68:71] offset:4608
	s_waitcnt vmcnt(13)
	ds_write_b128 v164, v[72:75] offset:9216
	s_waitcnt vmcnt(12)
	ds_write_b128 v164, v[76:79] offset:13824
	s_waitcnt vmcnt(11)
	ds_write_b128 v164, v[80:83] offset:36864
	s_waitcnt vmcnt(10)
	ds_write_b128 v164, v[92:95] offset:41472
	s_waitcnt vmcnt(9)
	ds_write_b128 v164, v[100:103] offset:46080
	s_waitcnt vmcnt(8)
	ds_write_b128 v164, v[112:115] offset:50688
	s_waitcnt lgkmcnt(0)
	s_barrier
	s_branch .LBB0_1310

.LBB0_1318:
	s_cmp_eq_u32 s27, 0
	s_cbranch_scc1 .Lsk_epi
	s_nop 7
	s_nop 7
	v_lshlrev_b32_e32 v128, 4, v186
	v_add_u32_e32 v129, 0x1000, v128
	v_add_u32_e32 v130, 0x2000, v128
	v_add_u32_e32 v131, 0x3000, v128
	v_add_u32_e32 v132, 0x4000, v128
	v_add_u32_e32 v133, 0x5000, v128
	v_add_u32_e32 v134, 0x6000, v128
	v_add_u32_e32 v135, 0x7000, v128
	v_add_u32_e32 v136, 0x8000, v128
	v_add_u32_e32 v137, 0x9000, v128
	v_add_u32_e32 v138, 0xa000, v128
	v_add_u32_e32 v139, 0xb000, v128
	v_add_u32_e32 v140, 0xc000, v128
	v_add_u32_e32 v141, 0xd000, v128
	v_add_u32_e32 v142, 0xe000, v128
	v_add_u32_e32 v143, 0xf000, v128
	s_cmp_eq_u32 s26, 0
	s_cbranch_scc1 .Lsk_main
	s_mul_i32 s30, s18, 3
	s_add_i32 s30, s30, s26
	s_add_i32 s30, s30, -1
	s_lshl_b32 s30, s30, 16
	s_add_u32 s30, s30, 0x9a00000
	s_add_u32 s30, s16, s30
	s_addc_u32 s31, s17, 0
	global_store_dwordx4 v128, v[0:3], s[30:31] sc0 sc1
	global_store_dwordx4 v129, v[4:7], s[30:31] sc0 sc1
	global_store_dwordx4 v130, v[8:11], s[30:31] sc0 sc1
	global_store_dwordx4 v131, v[12:15], s[30:31] sc0 sc1
	global_store_dwordx4 v132, v[16:19], s[30:31] sc0 sc1
	global_store_dwordx4 v133, v[20:23], s[30:31] sc0 sc1
	global_store_dwordx4 v134, v[24:27], s[30:31] sc0 sc1
	global_store_dwordx4 v135, v[28:31], s[30:31] sc0 sc1
	global_store_dwordx4 v136, v[32:35], s[30:31] sc0 sc1
	global_store_dwordx4 v137, v[36:39], s[30:31] sc0 sc1
	global_store_dwordx4 v138, v[40:43], s[30:31] sc0 sc1
	global_store_dwordx4 v139, v[44:47], s[30:31] sc0 sc1
	global_store_dwordx4 v140, v[48:51], s[30:31] sc0 sc1
	global_store_dwordx4 v141, v[52:55], s[30:31] sc0 sc1
	global_store_dwordx4 v142, v[56:59], s[30:31] sc0 sc1
	global_store_dwordx4 v143, v[60:63], s[30:31] sc0 sc1
	s_waitcnt vmcnt(0)
	s_barrier
	s_add_u32 s30, s16, 0xf000080
	s_addc_u32 s31, s17, 0
	v_mov_b32_e32 v65, s18
	v_lshlrev_b32_e32 v65, 2, v65
	v_mov_b32_e32 v64, 1
	v_cmp_eq_u32_e32 vcc, 0, v186
	s_and_saveexec_b64 s[32:33], vcc
	global_atomic_add v65, v64, s[30:31]
	s_or_b64 exec, exec, s[32:33]
	s_branch .LBB0_1574
.Lsk_main:
	s_add_u32 s30, s16, 0xf000080
	s_addc_u32 s31, s17, 0
	v_mov_b32_e32 v144, s18
	v_lshlrev_b32_e32 v144, 2, v144
	s_mov_b32 s32, 0
.Lsk_poll:
	global_load_dword v146, v144, s[30:31] sc1
	s_waitcnt vmcnt(0)
	v_readfirstlane_b32 s33, v146
	s_nop 1
	s_cmp_ge_u32 s33, 3
	s_cbranch_scc1 .Lsk_got
	s_sleep 2
	s_add_i32 s32, s32, 1
	s_cmp_lt_u32 s32, 0x2000
	s_cbranch_scc1 .Lsk_poll
.Lsk_got:
	s_mul_i32 s32, s18, 3
	s_lshl_b32 s32, s32, 16
	s_add_u32 s32, s32, 0x9a00000
	s_add_u32 s32, s16, s32
	s_addc_u32 s33, s17, 0
	global_load_dwordx4 v[64:67], v128, s[32:33] sc0 sc1
	global_load_dwordx4 v[68:71], v129, s[32:33] sc0 sc1
	global_load_dwordx4 v[72:75], v130, s[32:33] sc0 sc1
	global_load_dwordx4 v[76:79], v131, s[32:33] sc0 sc1
	global_load_dwordx4 v[80:83], v132, s[32:33] sc0 sc1
	global_load_dwordx4 v[84:87], v133, s[32:33] sc0 sc1
	global_load_dwordx4 v[88:91], v134, s[32:33] sc0 sc1
	global_load_dwordx4 v[92:95], v135, s[32:33] sc0 sc1
	global_load_dwordx4 v[96:99], v136, s[32:33] sc0 sc1
	global_load_dwordx4 v[100:103], v137, s[32:33] sc0 sc1
	global_load_dwordx4 v[104:107], v138, s[32:33] sc0 sc1
	global_load_dwordx4 v[108:111], v139, s[32:33] sc0 sc1
	global_load_dwordx4 v[112:115], v140, s[32:33] sc0 sc1
	global_load_dwordx4 v[116:119], v141, s[32:33] sc0 sc1
	global_load_dwordx4 v[120:123], v142, s[32:33] sc0 sc1
	global_load_dwordx4 v[124:127], v143, s[32:33] sc0 sc1
	s_add_u32 s32, s32, 0x10000
	s_addc_u32 s33, s33, 0
	s_waitcnt vmcnt(15)
	v_add_f32_e32 v0, v0, v64
	v_add_f32_e32 v1, v1, v65
	v_add_f32_e32 v2, v2, v66
	v_add_f32_e32 v3, v3, v67
	s_waitcnt vmcnt(14)
	v_add_f32_e32 v4, v4, v68
	v_add_f32_e32 v5, v5, v69
	v_add_f32_e32 v6, v6, v70
	v_add_f32_e32 v7, v7, v71
	s_waitcnt vmcnt(13)
	v_add_f32_e32 v8, v8, v72
	v_add_f32_e32 v9, v9, v73
	v_add_f32_e32 v10, v10, v74
	v_add_f32_e32 v11, v11, v75
	s_waitcnt vmcnt(12)
	v_add_f32_e32 v12, v12, v76
	v_add_f32_e32 v13, v13, v77
	v_add_f32_e32 v14, v14, v78
	v_add_f32_e32 v15, v15, v79
	s_waitcnt vmcnt(11)
	v_add_f32_e32 v16, v16, v80
	v_add_f32_e32 v17, v17, v81
	v_add_f32_e32 v18, v18, v82
	v_add_f32_e32 v19, v19, v83
	s_waitcnt vmcnt(10)
	v_add_f32_e32 v20, v20, v84
	v_add_f32_e32 v21, v21, v85
	v_add_f32_e32 v22, v22, v86
	v_add_f32_e32 v23, v23, v87
	s_waitcnt vmcnt(9)
	v_add_f32_e32 v24, v24, v88
	v_add_f32_e32 v25, v25, v89
	v_add_f32_e32 v26, v26, v90
	v_add_f32_e32 v27, v27, v91
	s_waitcnt vmcnt(8)
	v_add_f32_e32 v28, v28, v92
	v_add_f32_e32 v29, v29, v93
	v_add_f32_e32 v30, v30, v94
	v_add_f32_e32 v31, v31, v95
	global_load_dwordx4 v[64:67], v128, s[32:33] sc0 sc1
	global_load_dwordx4 v[68:71], v129, s[32:33] sc0 sc1
	global_load_dwordx4 v[72:75], v130, s[32:33] sc0 sc1
	global_load_dwordx4 v[76:79], v131, s[32:33] sc0 sc1
	global_load_dwordx4 v[80:83], v132, s[32:33] sc0 sc1
	global_load_dwordx4 v[84:87], v133, s[32:33] sc0 sc1
	global_load_dwordx4 v[88:91], v134, s[32:33] sc0 sc1
	global_load_dwordx4 v[92:95], v135, s[32:33] sc0 sc1
	s_waitcnt vmcnt(15)
	v_add_f32_e32 v32, v32, v96
	v_add_f32_e32 v33, v33, v97
	v_add_f32_e32 v34, v34, v98
	v_add_f32_e32 v35, v35, v99
	s_waitcnt vmcnt(14)
	v_add_f32_e32 v36, v36, v100
	v_add_f32_e32 v37, v37, v101
	v_add_f32_e32 v38, v38, v102
	v_add_f32_e32 v39, v39, v103
	s_waitcnt vmcnt(13)
	v_add_f32_e32 v40, v40, v104
	v_add_f32_e32 v41, v41, v105
	v_add_f32_e32 v42, v42, v106
	v_add_f32_e32 v43, v43, v107
	s_waitcnt vmcnt(12)
	v_add_f32_e32 v44, v44, v108
	v_add_f32_e32 v45, v45, v109
	v_add_f32_e32 v46, v46, v110
	v_add_f32_e32 v47, v47, v111
	s_waitcnt vmcnt(11)
	v_add_f32_e32 v48, v48, v112
	v_add_f32_e32 v49, v49, v113
	v_add_f32_e32 v50, v50, v114
	v_add_f32_e32 v51, v51, v115
	s_waitcnt vmcnt(10)
	v_add_f32_e32 v52, v52, v116
	v_add_f32_e32 v53, v53, v117
	v_add_f32_e32 v54, v54, v118
	v_add_f32_e32 v55, v55, v119
	s_waitcnt vmcnt(9)
	v_add_f32_e32 v56, v56, v120
	v_add_f32_e32 v57, v57, v121
	v_add_f32_e32 v58, v58, v122
	v_add_f32_e32 v59, v59, v123
	s_waitcnt vmcnt(8)
	v_add_f32_e32 v60, v60, v124
	v_add_f32_e32 v61, v61, v125
	v_add_f32_e32 v62, v62, v126
	v_add_f32_e32 v63, v63, v127
	global_load_dwordx4 v[96:99], v136, s[32:33] sc0 sc1
	global_load_dwordx4 v[100:103], v137, s[32:33] sc0 sc1
	global_load_dwordx4 v[104:107], v138, s[32:33] sc0 sc1
	global_load_dwordx4 v[108:111], v139, s[32:33] sc0 sc1
	global_load_dwordx4 v[112:115], v140, s[32:33] sc0 sc1
	global_load_dwordx4 v[116:119], v141, s[32:33] sc0 sc1
	global_load_dwordx4 v[120:123], v142, s[32:33] sc0 sc1
	global_load_dwordx4 v[124:127], v143, s[32:33] sc0 sc1
	s_add_u32 s32, s32, 0x10000
	s_addc_u32 s33, s33, 0
	s_waitcnt vmcnt(15)
	v_add_f32_e32 v0, v0, v64
	v_add_f32_e32 v1, v1, v65
	v_add_f32_e32 v2, v2, v66
	v_add_f32_e32 v3, v3, v67
	s_waitcnt vmcnt(14)
	v_add_f32_e32 v4, v4, v68
	v_add_f32_e32 v5, v5, v69
	v_add_f32_e32 v6, v6, v70
	v_add_f32_e32 v7, v7, v71
	s_waitcnt vmcnt(13)
	v_add_f32_e32 v8, v8, v72
	v_add_f32_e32 v9, v9, v73
	v_add_f32_e32 v10, v10, v74
	v_add_f32_e32 v11, v11, v75
	s_waitcnt vmcnt(12)
	v_add_f32_e32 v12, v12, v76
	v_add_f32_e32 v13, v13, v77
	v_add_f32_e32 v14, v14, v78
	v_add_f32_e32 v15, v15, v79
	s_waitcnt vmcnt(11)
	v_add_f32_e32 v16, v16, v80
	v_add_f32_e32 v17, v17, v81
	v_add_f32_e32 v18, v18, v82
	v_add_f32_e32 v19, v19, v83
	s_waitcnt vmcnt(10)
	v_add_f32_e32 v20, v20, v84
	v_add_f32_e32 v21, v21, v85
	v_add_f32_e32 v22, v22, v86
	v_add_f32_e32 v23, v23, v87
	s_waitcnt vmcnt(9)
	v_add_f32_e32 v24, v24, v88
	v_add_f32_e32 v25, v25, v89
	v_add_f32_e32 v26, v26, v90
	v_add_f32_e32 v27, v27, v91
	s_waitcnt vmcnt(8)
	v_add_f32_e32 v28, v28, v92
	v_add_f32_e32 v29, v29, v93
	v_add_f32_e32 v30, v30, v94
	v_add_f32_e32 v31, v31, v95
	global_load_dwordx4 v[64:67], v128, s[32:33] sc0 sc1
	global_load_dwordx4 v[68:71], v129, s[32:33] sc0 sc1
	global_load_dwordx4 v[72:75], v130, s[32:33] sc0 sc1
	global_load_dwordx4 v[76:79], v131, s[32:33] sc0 sc1
	global_load_dwordx4 v[80:83], v132, s[32:33] sc0 sc1
	global_load_dwordx4 v[84:87], v133, s[32:33] sc0 sc1
	global_load_dwordx4 v[88:91], v134, s[32:33] sc0 sc1
	global_load_dwordx4 v[92:95], v135, s[32:33] sc0 sc1
	s_waitcnt vmcnt(15)
	v_add_f32_e32 v32, v32, v96
	v_add_f32_e32 v33, v33, v97
	v_add_f32_e32 v34, v34, v98
	v_add_f32_e32 v35, v35, v99
	s_waitcnt vmcnt(14)
	v_add_f32_e32 v36, v36, v100
	v_add_f32_e32 v37, v37, v101
	v_add_f32_e32 v38, v38, v102
	v_add_f32_e32 v39, v39, v103
	s_waitcnt vmcnt(13)
	v_add_f32_e32 v40, v40, v104
	v_add_f32_e32 v41, v41, v105
	v_add_f32_e32 v42, v42, v106
	v_add_f32_e32 v43, v43, v107
	s_waitcnt vmcnt(12)
	v_add_f32_e32 v44, v44, v108
	v_add_f32_e32 v45, v45, v109
	v_add_f32_e32 v46, v46, v110
	v_add_f32_e32 v47, v47, v111
	s_waitcnt vmcnt(11)
	v_add_f32_e32 v48, v48, v112
	v_add_f32_e32 v49, v49, v113
	v_add_f32_e32 v50, v50, v114
	v_add_f32_e32 v51, v51, v115
	s_waitcnt vmcnt(10)
	v_add_f32_e32 v52, v52, v116
	v_add_f32_e32 v53, v53, v117
	v_add_f32_e32 v54, v54, v118
	v_add_f32_e32 v55, v55, v119
	s_waitcnt vmcnt(9)
	v_add_f32_e32 v56, v56, v120
	v_add_f32_e32 v57, v57, v121
	v_add_f32_e32 v58, v58, v122
	v_add_f32_e32 v59, v59, v123
	s_waitcnt vmcnt(8)
	v_add_f32_e32 v60, v60, v124
	v_add_f32_e32 v61, v61, v125
	v_add_f32_e32 v62, v62, v126
	v_add_f32_e32 v63, v63, v127
	global_load_dwordx4 v[96:99], v136, s[32:33] sc0 sc1
	global_load_dwordx4 v[100:103], v137, s[32:33] sc0 sc1
	global_load_dwordx4 v[104:107], v138, s[32:33] sc0 sc1
	global_load_dwordx4 v[108:111], v139, s[32:33] sc0 sc1
	global_load_dwordx4 v[112:115], v140, s[32:33] sc0 sc1
	global_load_dwordx4 v[116:119], v141, s[32:33] sc0 sc1
	global_load_dwordx4 v[120:123], v142, s[32:33] sc0 sc1
	global_load_dwordx4 v[124:127], v143, s[32:33] sc0 sc1
	s_waitcnt vmcnt(15)
	v_add_f32_e32 v0, v0, v64
	v_add_f32_e32 v1, v1, v65
	v_add_f32_e32 v2, v2, v66
	v_add_f32_e32 v3, v3, v67
	s_waitcnt vmcnt(14)
	v_add_f32_e32 v4, v4, v68
	v_add_f32_e32 v5, v5, v69
	v_add_f32_e32 v6, v6, v70
	v_add_f32_e32 v7, v7, v71
	s_waitcnt vmcnt(13)
	v_add_f32_e32 v8, v8, v72
	v_add_f32_e32 v9, v9, v73
	v_add_f32_e32 v10, v10, v74
	v_add_f32_e32 v11, v11, v75
	s_waitcnt vmcnt(12)
	v_add_f32_e32 v12, v12, v76
	v_add_f32_e32 v13, v13, v77
	v_add_f32_e32 v14, v14, v78
	v_add_f32_e32 v15, v15, v79
	s_waitcnt vmcnt(11)
	v_add_f32_e32 v16, v16, v80
	v_add_f32_e32 v17, v17, v81
	v_add_f32_e32 v18, v18, v82
	v_add_f32_e32 v19, v19, v83
	s_waitcnt vmcnt(10)
	v_add_f32_e32 v20, v20, v84
	v_add_f32_e32 v21, v21, v85
	v_add_f32_e32 v22, v22, v86
	v_add_f32_e32 v23, v23, v87
	s_waitcnt vmcnt(9)
	v_add_f32_e32 v24, v24, v88
	v_add_f32_e32 v25, v25, v89
	v_add_f32_e32 v26, v26, v90
	v_add_f32_e32 v27, v27, v91
	s_waitcnt vmcnt(8)
	v_add_f32_e32 v28, v28, v92
	v_add_f32_e32 v29, v29, v93
	v_add_f32_e32 v30, v30, v94
	v_add_f32_e32 v31, v31, v95
	s_waitcnt vmcnt(7)
	v_add_f32_e32 v32, v32, v96
	v_add_f32_e32 v33, v33, v97
	v_add_f32_e32 v34, v34, v98
	v_add_f32_e32 v35, v35, v99
	s_waitcnt vmcnt(6)
	v_add_f32_e32 v36, v36, v100
	v_add_f32_e32 v37, v37, v101
	v_add_f32_e32 v38, v38, v102
	v_add_f32_e32 v39, v39, v103
	s_waitcnt vmcnt(5)
	v_add_f32_e32 v40, v40, v104
	v_add_f32_e32 v41, v41, v105
	v_add_f32_e32 v42, v42, v106
	v_add_f32_e32 v43, v43, v107
	s_waitcnt vmcnt(4)
	v_add_f32_e32 v44, v44, v108
	v_add_f32_e32 v45, v45, v109
	v_add_f32_e32 v46, v46, v110
	v_add_f32_e32 v47, v47, v111
	s_waitcnt vmcnt(3)
	v_add_f32_e32 v48, v48, v112
	v_add_f32_e32 v49, v49, v113
	v_add_f32_e32 v50, v50, v114
	v_add_f32_e32 v51, v51, v115
	s_waitcnt vmcnt(2)
	v_add_f32_e32 v52, v52, v116
	v_add_f32_e32 v53, v53, v117
	v_add_f32_e32 v54, v54, v118
	v_add_f32_e32 v55, v55, v119
	s_waitcnt vmcnt(1)
	v_add_f32_e32 v56, v56, v120
	v_add_f32_e32 v57, v57, v121
	v_add_f32_e32 v58, v58, v122
	v_add_f32_e32 v59, v59, v123
	s_waitcnt vmcnt(0)
	v_add_f32_e32 v60, v60, v124
	v_add_f32_e32 v61, v61, v125
	v_add_f32_e32 v62, v62, v126
	v_add_f32_e32 v63, v63, v127
	s_barrier
	v_mov_b32_e32 v145, -3
	v_cmp_eq_u32_e32 vcc, 0, v186
	s_and_saveexec_b64 s[32:33], vcc
	global_atomic_add v144, v145, s[30:31]
	s_or_b64 exec, exec, s[32:33]
